# v122 + dattn: one static s_setprio 1 for waves 4-7 over the unit loop
# speedup vs baseline: 1.0031x; 1.0031x over previous
.LBB0_1390:
	v_readlane_b32 s12, v244, 47
	v_readlane_b32 s14, v244, 49
	s_bitcmp0_b32 s14, 0
	s_cselect_b64 s[0:1], -1, 0
	s_cmpk_lt_i32 s69, 0x600
	s_cselect_b64 s[2:3], -1, 0
	s_and_b64 s[0:1], s[0:1], s[2:3]
	v_readlane_b32 s13, v244, 48
	s_andn2_b64 vcc, exec, s[0:1]
	v_readlane_b32 s15, v244, 50
	s_cbranch_vccnz .LBB0_1416
	v_mbcnt_lo_u32_b32 v0, -1, 0
	v_mbcnt_hi_u32_b32 v0, -1, v0
	v_and_b32_e32 v1, 64, v0
	v_add_u32_e32 v1, 64, v1
	v_xor_b32_e32 v2, 1, v0
	v_cmp_lt_i32_e32 vcc, v2, v1
	v_writelane_b32 v244, s89, 55
	s_movk_i32 s0, 0x1ff
	v_cndmask_b32_e32 v2, v0, v2, vcc
	v_lshlrev_b32_e32 v81, 2, v2
	v_xor_b32_e32 v2, 2, v0
	v_cmp_lt_i32_e32 vcc, v2, v1
	v_readlane_b32 s4, v244, 0
	v_readlane_b32 s10, v244, 6
	v_cndmask_b32_e32 v2, v0, v2, vcc
	v_lshlrev_b32_e32 v85, 2, v2
	v_xor_b32_e32 v2, 4, v0
	v_cmp_lt_i32_e32 vcc, v2, v1
	v_readlane_b32 s11, v244, 7
	s_add_u32 s90, s10, 0xf000000
	v_cndmask_b32_e32 v2, v0, v2, vcc
	v_lshlrev_b32_e32 v86, 2, v2
	v_xor_b32_e32 v2, 8, v0
	v_cmp_lt_i32_e32 vcc, v2, v1
	s_addc_u32 s91, s11, 0
	s_add_u32 s92, s10, 0x12000000
	v_cndmask_b32_e32 v2, v0, v2, vcc
	v_lshlrev_b32_e32 v87, 2, v2
	v_xor_b32_e32 v2, 16, v0
	v_cmp_lt_i32_e32 vcc, v2, v1
	s_addc_u32 s93, s11, 0
	s_add_u32 s94, s10, 0x15000000
	v_cndmask_b32_e32 v2, v0, v2, vcc
	v_lshlrev_b32_e32 v88, 2, v2
	v_xor_b32_e32 v2, 32, v0
	v_cmp_lt_i32_e32 vcc, v2, v1
	v_readlane_b32 s9, v244, 5
	s_addc_u32 s95, s11, 0
	v_cndmask_b32_e32 v0, v0, v2, vcc
	v_lshlrev_b32_e32 v89, 2, v0
	v_lshlrev_b32_e32 v0, 4, v182
	v_and_b32_e32 v90, 0x70, v0
	v_add_u32_e32 v0, 0x200, v182
	v_lshrrev_b32_e32 v92, 3, v0
	v_add_u32_e32 v0, 0x600, v182
	v_cmp_lt_u32_e32 vcc, s0, v182
	s_lshl_b32 s0, s88, 4
	v_readlane_b32 s8, v244, 4
	v_lshrrev_b32_e32 v94, 3, v0
	v_add_u32_e32 v0, 0xa00, v182
	v_mov_b32_e32 v2, 0xfffffe80
	s_and_b32 s9, s0, 48
	v_or_b32_e32 v9, 0x400, v182
	s_movk_i32 s0, 0x5ff
	v_and_b32_e32 v73, 15, v182
	s_lshl_b32 s8, s88, 5
	v_lshrrev_b32_e32 v1, 3, v0
	v_cndmask_b32_e64 v96, 0, 1, vcc
	v_cndmask_b32_e32 v2, 0, v2, vcc
	v_lshrrev_b32_e32 v10, 3, v9
	v_cmp_lt_u32_e32 vcc, s0, v9
	v_mov_b32_e32 v9, 0xffffff40
	v_mul_u32_u24_e32 v0, 0xaab, v0
	v_readlane_b32 s6, v244, 2
	v_cndmask_b32_e32 v9, 0, v9, vcc
	v_lshrrev_b32_e32 v105, 22, v0
	v_or_b32_e32 v0, s8, v73
	s_movk_i32 s1, 0x110
	s_add_i32 s4, 0, 0x11000
	s_mul_i32 s2, s88, 0x1200
	s_lshr_b32 s6, s87, 8
	s_movk_i32 s0, 0xff40
	v_add_u32_e32 v104, v9, v10
	v_mul_u32_u24_e32 v9, 0x90, v10
	v_mul_lo_u32 v10, v0, s1
	v_lshl_add_u32 v107, v0, 2, s4
	v_or_b32_e32 v0, s9, v73
	v_readlane_b32 s7, v244, 3
	v_lshrrev_b32_e32 v91, 3, v182
	v_add_u32_e32 v97, v2, v1
	v_add_u32_e32 v2, 0, v90
	s_movk_i32 s96, 0x90
	v_mad_i32_i24 v106, v105, s0, v1
	s_add_i32 s0, s2, 0
	v_lshl_add_u32 v0, v0, 2, s6
	s_lshl_b32 s7, s88, 1
	v_mad_u32_u24 v4, v91, s96, v2
	v_mul_u32_u24_e32 v7, 0x90, v1
	s_add_i32 s0, s0, 0x11400
	v_mul_lo_u32 v1, v0, s1
	v_lshl_add_u32 v110, v0, 2, s4
	v_lshrrev_b32_e32 v0, 3, v144
	v_readlane_b32 s16, v244, 15
	v_add_u32_e32 v98, 0x12000, v4
	v_add_u32_e32 v99, 0x16800, v4
	v_lshrrev_b32_e32 v4, 2, v144
	s_or_b32 s12, s7, 1
	v_add_u32_e32 v109, 0, v1
	v_or_b32_e32 v112, 0xffffffc0, v0
	v_mov_b32_e32 v1, s0
	v_mul_u32_u24_e32 v14, 0x90, v0
	v_lshlrev_b32_e32 v0, 4, v73
	v_readlane_b32 s17, v244, 16
	v_mad_u32_u24 v13, v4, s96, v1
	v_add_u32_e32 v1, s7, v0
	v_add_u32_e32 v0, s12, v0
	v_lshrrev_b32_e32 v123, 1, v182
	v_and_b32_e32 v17, 1, v182
	v_readlane_b32 s5, v244, 1
	v_lshlrev_b32_e32 v74, 2, v144
	v_mov_b32_e32 v75, 0
	v_readlane_b32 s18, v244, 17
	v_readlane_b32 s19, v244, 18
	v_readlane_b32 s20, v244, 19
	v_readlane_b32 s21, v244, 20
	v_readlane_b32 s22, v244, 21
	v_readlane_b32 s23, v244, 22
	v_readlane_b32 s24, v244, 23
	v_readlane_b32 s25, v244, 24
	v_readlane_b32 s26, v244, 25
	v_readlane_b32 s27, v244, 26
	v_readlane_b32 s28, v244, 27
	v_readlane_b32 s29, v244, 28
	v_readlane_b32 s30, v244, 29
	v_readlane_b32 s31, v244, 30
	s_cmp_lt_u32 s88, 4
	s_cbranch_scc1 .Ldprio_n
	s_setprio 1
.Ldprio_n:
	v_writelane_b32 v244, s88, 56
	v_cmp_lt_u32_e64 s[16:17], 15, v144
	v_add_u32_e32 v12, s0, v90
	v_mul_lo_u32 v15, v1, s1
	v_mul_lo_u32 v16, v0, s1
	v_mad_u32_u24 v18, v123, s1, 0
	v_cmp_eq_u32_e64 s[0:1], 0, v17
	v_lshl_add_u64 v[76:77], s[24:25], 0, v[74:75]
	v_lshl_add_u64 v[78:79], s[26:27], 0, v[74:75]
	v_writelane_b32 v244, s16, 57
	s_bitcmp0_b32 s14, 1
	v_lshlrev_b32_e32 v74, 2, v123
	v_writelane_b32 v243, s0, 1
	v_and_b32_e32 v101, 12, v4
	v_writelane_b32 v244, s17, 58
	s_cselect_b64 s[14:15], -1, 0
	v_lshl_add_u32 v121, v1, 2, s4
	v_lshl_add_u32 v122, v0, 2, s4
	v_writelane_b32 v243, s1, 2
	v_lshl_add_u64 v[0:1], s[10:11], 0, v[74:75]
	s_mov_b64 s[0:1], 0x1fb50000
	v_writelane_b32 v244, s14, 59
	v_lshl_add_u64 v[82:83], v[0:1], 0, s[0:1]
	v_or_b32_e32 v1, s8, v101
	v_lshlrev_b32_e32 v8, 3, v182
	v_writelane_b32 v244, s15, 60
	v_writelane_b32 v243, s8, 3
	v_subrev_u32_e32 v125, 64, v1
	v_mov_b32_e32 v1, s2
	v_and_b32_e32 v8, 24, v8
	s_mul_i32 s3, s6, 0xc0
	v_writelane_b32 v244, s7, 61
	v_lshlrev_b32_e32 v19, 7, v17
	v_lshlrev_b32_e32 v0, 5, v17
	v_mad_u32_u24 v17, v73, s96, v1
	v_mad_u32_u24 v1, v4, s96, v1
	v_writelane_b32 v243, s87, 5
	s_bfe_u32 s7, s87, 0x20006
	s_mul_i32 s0, s6, 0x6c00
	s_mov_b32 s5, s69
	v_and_b32_e32 v100, 48, v182
	v_add3_u32 v127, v1, v8, 0
	s_mulk_i32 s7, 0x900
	v_mov_b32_e32 v1, s0
	v_writelane_b32 v243, s9, 7
	s_or_b32 s0, s3, s9
	v_mul_u32_u24_e32 v3, 0x90, v91
	v_mul_u32_u24_e32 v5, 0x90, v92
	v_mul_u32_u24_e32 v6, 0x90, v94
	v_add_u32_e32 v80, 0, v100
	v_cmp_gt_u32_e64 s[40:41], 16, v144
	v_add_u32_e32 v11, 0x220, v109
	v_add3_u32 v126, v17, v100, 0
	v_mad_u32_u24 v17, v4, s96, v1
	v_or_b32_e32 v4, s0, v4
	v_or_b32_e32 v131, s0, v73
	s_add_i32 s0, s7, 0
	v_writelane_b32 v243, s5, 9
	v_or_b32_e32 v93, 0x80, v91
	v_or_b32_e32 v95, 0x100, v91
	v_or_b32_e32 v72, 16, v73
	v_or_b32_e32 v102, 0xffffffc0, v101
	v_cndmask_b32_e64 v103, 0, 1, vcc
	v_add_u32_e32 v108, 64, v107
	v_add_u32_e32 v111, 8, v110
	v_or_b32_e32 v113, 0xffffffc0, v73
	v_or_b32_e32 v114, 0xffffffd0, v73
	v_or_b32_e32 v115, 0xffffffe0, v73
	v_or_b32_e32 v116, -16, v182
	v_or_b32_e32 v117, 32, v73
	v_or_b32_e32 v118, 48, v144
	v_or_b32_e32 v119, 64, v73
	v_or_b32_e32 v120, 0x50, v73
	v_add_u32_e32 v124, s4, v74
	v_add_u32_e32 v84, 0, v8
	v_or_b32_e32 v128, s9, v101
	v_add3_u32 v129, v17, v8, 0
	v_add_u32_e32 v130, 0x180, v4
	v_add_u32_e32 v132, s0, v100
	v_mad_u32_u24 v133, v73, s96, v1
	s_mov_b32 s4, 0x3e38aa3b
	s_movk_i32 s39, 0xbf
	v_add_u32_e32 v134, v11, v100
	v_add_u32_e32 v135, v80, v15
	v_add_u32_e32 v136, v80, v16
	v_add_u32_e32 v137, v18, v19
	v_lshlrev_b32_e32 v74, 1, v0
	v_add_u32_e32 v138, v2, v3
	v_add_u32_e32 v139, v2, v5
	v_add_u32_e32 v140, v2, v6
	v_add_u32_e32 v141, v2, v7
	v_add_u32_e32 v142, v2, v9
	v_add_u32_e32 v143, v80, v10
	v_add_u32_e32 v146, v12, v14
	v_add_u32_e32 v147, v13, v8
	v_writelane_b32 v243, s40, 10
	v_writelane_b32 v244, s12, 63
	s_nop 0
	v_writelane_b32 v243, s41, 11
	s_branch .LBB0_1393

.LBB0_1415:
	s_setprio 0
	v_readlane_b32 s12, v244, 47
	v_readlane_b32 s13, v244, 48
	v_readlane_b32 s88, v244, 56
	v_readlane_b32 s69, v243, 9
	v_readlane_b32 s89, v244, 55
	v_readlane_b32 s87, v243, 5
	v_readlane_b32 s14, v244, 49
	v_readlane_b32 s15, v244, 50
